# v46 + P1 epilogue mid wait relaxed to vmcnt(3)
# speedup vs baseline: 1.0381x; 1.0038x over previous
.LBB0_153:
	s_or_b64 exec, exec, s[84:85]
	v_mul_f32_e32 v5, 0xbfb8aa3b, v108
	v_exp_f32_e32 v5, v5
	v_mul_f32_e32 v72, 0xbfb8aa3b, v109
	v_exp_f32_e32 v72, v72
	v_mul_f32_e32 v9, v124, v108
	v_add_f32_e32 v5, 1.0, v5
	v_rcp_f32_e32 v5, v5
	v_add_f32_e32 v72, 1.0, v72
	v_mul_f32_e32 v108, 0xbfb8aa3b, v111
	v_rcp_f32_e32 v72, v72
	v_mul_f32_e32 v5, v9, v5
	v_mul_f32_e32 v9, 0xbfb8aa3b, v110
	v_exp_f32_e32 v9, v9
	v_exp_f32_e32 v108, v108
	v_mul_f32_e32 v73, v125, v109
	v_mul_f32_e32 v73, v73, v72
	v_add_f32_e32 v9, 1.0, v9
	v_rcp_f32_e32 v9, v9
	v_add_f32_e32 v72, 1.0, v108
	v_rcp_f32_e32 v72, v72
	v_mul_f32_e32 v108, v126, v110
	v_mul_f32_e32 v110, v108, v9
	v_mul_f32_e32 v9, v127, v111
	v_pk_mul_f32 v[104:105], v[116:117], v[104:105]
	v_mul_f32_e32 v111, v9, v72
	v_mov_b32_dpp v9, v128 row_ror:1 row_mask:0xf bank_mask:0xf
	v_mov_b32_dpp v116, v104 row_ror:1 row_mask:0xf bank_mask:0xf
	v_mov_b32_dpp v117, v104 row_ror:2 row_mask:0xf bank_mask:0xf
	v_mov_b32_dpp v108, v128 row_ror:2 row_mask:0xf bank_mask:0xf
	s_waitcnt vmcnt(3)
	v_cndmask_b32_e64 v115, v117, v108, s[8:9]
	v_cndmask_b32_e64 v113, v116, v9, s[6:7]
	v_mov_b32_e32 v108, v104
	v_mov_b32_e32 v109, v100
	v_pk_mul_f32 v[108:109], v[108:109], v[112:113]
	v_pk_mul_f32 v[106:107], v[118:119], v[106:107]
	v_fma_f32 v9, v96, v115, v109
	v_add_f32_e32 v9, v108, v9
	v_mul_f32_e32 v108, v5, v9
	v_mov_b32_dpp v109, v105 row_ror:1 row_mask:0xf bank_mask:0xf
	v_mov_b32_dpp v118, v105 row_ror:2 row_mask:0xf bank_mask:0xf
	v_mov_b32_dpp v5, v129 row_ror:1 row_mask:0xf bank_mask:0xf
	v_mov_b32_dpp v9, v129 row_ror:2 row_mask:0xf bank_mask:0xf
	v_cndmask_b32_e64 v113, v118, v9, s[8:9]
	v_cndmask_b32_e64 v9, v109, v5, s[6:7]
	v_mov_b32_e32 v104, v105
	v_mov_b32_e32 v105, v101
	v_pk_mul_f32 v[104:105], v[104:105], v[8:9]
	v_mov_b32_dpp v119, v106 row_ror:1 row_mask:0xf bank_mask:0xf
	v_fma_f32 v5, v97, v113, v105
	v_add_f32_e32 v5, v104, v5
	v_mul_f32_e32 v9, v73, v5
	v_mov_b32_dpp v122, v106 row_ror:2 row_mask:0xf bank_mask:0xf
	v_mov_b32_dpp v5, v130 row_ror:1 row_mask:0xf bank_mask:0xf
	v_mov_b32_dpp v73, v130 row_ror:2 row_mask:0xf bank_mask:0xf
	v_cndmask_b32_e64 v115, v119, v5, s[6:7]
	v_mov_b32_e32 v104, v106
	v_mov_b32_e32 v105, v102
	v_cndmask_b32_e64 v73, v122, v73, s[8:9]
	v_pk_mul_f32 v[104:105], v[104:105], v[114:115]
	v_mov_b32_dpp v123, v107 row_ror:2 row_mask:0xf bank_mask:0xf
	v_fma_f32 v5, v98, v73, v105
	v_add_f32_e32 v5, v104, v5
	v_mul_f32_e32 v73, v110, v5
	v_mov_b32_dpp v110, v107 row_ror:1 row_mask:0xf bank_mask:0xf
	v_mov_b32_dpp v5, v131 row_ror:1 row_mask:0xf bank_mask:0xf
	v_mov_b32_dpp v106, v131 row_ror:2 row_mask:0xf bank_mask:0xf
	v_cndmask_b32_e64 v5, v110, v5, s[6:7]
	v_mov_b32_e32 v104, v107
	v_mov_b32_e32 v105, v103
	v_pk_mul_f32 v[104:105], v[104:105], v[4:5]
	v_cndmask_b32_e64 v5, v123, v106, s[8:9]
	v_fma_f32 v5, v99, v5, v105
	v_add_f32_e32 v5, v104, v5
	v_mul_f32_e32 v5, v111, v5
	v_cvt_pk_bf16_f32 v104, v108, v9
	v_cvt_pk_bf16_f32 v105, v73, v5
	v_mul_f32_e32 v5, 0xbfb8aa3b, v84
	v_or_b32_e32 v72, 16, v64
	v_exp_f32_e32 v5, v5
	v_mul_f32_e32 v9, 0xbfb8aa3b, v85
	v_ashrrev_i32_e32 v73, 31, v72
	v_exp_f32_e32 v9, v9
	v_lshlrev_b64 v[72:73], 11, v[72:73]
	v_lshl_add_u64 v[72:73], s[28:29], 0, v[72:73]
	v_lshlrev_b64 v[106:107], 1, v[170:171]
	v_lshl_add_u64 v[72:73], v[72:73], 0, v[106:107]
	v_add_f32_e32 v5, 1.0, v5
	global_store_dwordx2 v[72:73], v[104:105], off
	v_rcp_f32_e32 v5, v5
	v_add_f32_e32 v9, 1.0, v9
	v_mul_f32_e32 v73, 0xbfb8aa3b, v86
	v_rcp_f32_e32 v9, v9
	v_exp_f32_e32 v73, v73
	v_mul_f32_e32 v72, v92, v84
	v_mul_f32_e32 v84, 0xbfb8aa3b, v87
	v_exp_f32_e32 v84, v84
	v_mul_f32_e32 v5, v72, v5
	v_mul_f32_e32 v72, v93, v85
	v_mul_f32_e32 v92, v72, v9
	v_add_f32_e32 v9, 1.0, v73
	v_rcp_f32_e32 v9, v9
	v_add_f32_e32 v72, 1.0, v84
	v_rcp_f32_e32 v72, v72
	v_mul_f32_e32 v73, v94, v86
	v_pk_mul_f32 v[80:81], v[88:89], v[80:81]
	v_mul_f32_e32 v73, v73, v9
	v_mul_f32_e32 v9, v95, v87
	v_mov_b32_dpp v87, v80 row_ror:1 row_mask:0xf bank_mask:0xf
	v_mov_b32_dpp v88, v80 row_ror:2 row_mask:0xf bank_mask:0xf
	v_cndmask_b32_e64 v113, v87, v116, s[6:7]
	v_mov_b32_e32 v84, v80
	v_mov_b32_e32 v85, v100
	v_mul_f32_e32 v86, v9, v72
	v_cndmask_b32_e64 v9, v88, v117, s[8:9]
	v_pk_mul_f32 v[84:85], v[84:85], v[112:113]
	v_mov_b32_dpp v89, v81 row_ror:2 row_mask:0xf bank_mask:0xf
	v_fma_f32 v9, v96, v9, v85
	v_add_f32_e32 v9, v84, v9
	v_mov_b32_dpp v85, v81 row_ror:1 row_mask:0xf bank_mask:0xf
	v_mul_f32_e32 v84, v5, v9
	v_cndmask_b32_e64 v9, v85, v109, s[6:7]
	v_mov_b32_e32 v80, v81
	v_mov_b32_e32 v81, v101
	v_pk_mul_f32 v[82:83], v[90:91], v[82:83]
	v_cndmask_b32_e64 v5, v89, v118, s[8:9]
	v_pk_mul_f32 v[80:81], v[80:81], v[8:9]
	v_mov_b32_dpp v90, v82 row_ror:1 row_mask:0xf bank_mask:0xf
	v_fma_f32 v5, v97, v5, v81
	v_add_f32_e32 v5, v80, v5
	v_mov_b32_dpp v91, v82 row_ror:2 row_mask:0xf bank_mask:0xf
	v_cndmask_b32_e64 v115, v90, v119, s[6:7]
	v_mov_b32_e32 v80, v82
	v_mov_b32_e32 v81, v102
	v_mul_f32_e32 v9, v92, v5
	v_cndmask_b32_e64 v5, v91, v122, s[8:9]
	v_pk_mul_f32 v[80:81], v[80:81], v[114:115]
	v_mov_b32_dpp v82, v83 row_ror:1 row_mask:0xf bank_mask:0xf
	v_fma_f32 v5, v98, v5, v81
	v_add_f32_e32 v5, v80, v5
	v_mul_f32_e32 v73, v73, v5
	v_mov_b32_dpp v92, v83 row_ror:2 row_mask:0xf bank_mask:0xf
	v_cndmask_b32_e64 v5, v82, v110, s[6:7]
	v_mov_b32_e32 v80, v83
	v_mov_b32_e32 v81, v103
	v_pk_mul_f32 v[80:81], v[80:81], v[4:5]
	v_cndmask_b32_e64 v5, v92, v123, s[8:9]
	v_fma_f32 v5, v99, v5, v81
	v_add_f32_e32 v5, v80, v5
	v_mul_f32_e32 v5, v86, v5
	v_cvt_pk_bf16_f32 v80, v84, v9
	v_cvt_pk_bf16_f32 v81, v73, v5
	v_mul_f32_e32 v5, 0xbfb8aa3b, v68
	v_exp_f32_e32 v5, v5
	v_mul_f32_e32 v9, 0xbfb8aa3b, v69
	v_or_b32_e32 v72, 32, v64
	v_exp_f32_e32 v9, v9
	v_add_f32_e32 v5, 1.0, v5
	v_rcp_f32_e32 v5, v5
	v_ashrrev_i32_e32 v73, 31, v72
	v_lshlrev_b64 v[72:73], 11, v[72:73]
	v_lshl_add_u64 v[72:73], s[28:29], 0, v[72:73]
	v_mul_f32_e32 v68, v76, v68
	v_lshl_add_u64 v[72:73], v[72:73], 0, v[106:107]
	v_mul_f32_e32 v5, v68, v5
	v_mul_f32_e32 v68, v77, v69
	v_add_f32_e32 v9, 1.0, v9
	v_mul_f32_e32 v69, 0xbfb8aa3b, v70
	global_store_dwordx2 v[72:73], v[80:81], off
	v_rcp_f32_e32 v9, v9
	v_exp_f32_e32 v69, v69
	v_mul_f32_e32 v72, 0xbfb8aa3b, v71
	v_exp_f32_e32 v72, v72
	v_mul_f32_e32 v73, v68, v9
	v_add_f32_e32 v9, 1.0, v69
	v_rcp_f32_e32 v9, v9
	v_add_f32_e32 v68, 1.0, v72
	v_rcp_f32_e32 v68, v68
	v_mul_f32_e32 v69, v78, v70
	v_mul_f32_e32 v69, v69, v9
	v_mul_f32_e32 v9, v79, v71
	v_mul_f32_e32 v72, v9, v68
	v_mov_b32_dpp v70, v144 row_ror:2 row_mask:0xf bank_mask:0xf
	v_mov_b32_dpp v9, v144 row_ror:1 row_mask:0xf bank_mask:0xf
	v_pk_mul_f32 v[66:67], v[74:75], v[66:67]
	v_cndmask_b32_e64 v74, v70, v88, s[8:9]
	v_cndmask_b32_e64 v113, v9, v87, s[6:7]
	v_mov_b32_e32 v70, v144
	v_mov_b32_e32 v71, v100
	v_pk_mul_f32 v[70:71], v[70:71], v[112:113]
	v_or_b32_e32 v68, 48, v64
	v_fma_f32 v9, v96, v74, v71
	v_add_f32_e32 v9, v70, v9
	v_mul_f32_e32 v74, v5, v9
	v_mov_b32_dpp v5, v145 row_ror:1 row_mask:0xf bank_mask:0xf
	v_mov_b32_dpp v9, v145 row_ror:2 row_mask:0xf bank_mask:0xf
	v_cndmask_b32_e64 v75, v9, v89, s[8:9]
	v_cndmask_b32_e64 v9, v5, v85, s[6:7]
	v_mov_b32_e32 v70, v145
	v_mov_b32_e32 v71, v101
	v_pk_mul_f32 v[70:71], v[70:71], v[8:9]
	v_pk_mul_f32 v[50:51], v[58:59], v[50:51]
	v_fma_f32 v5, v97, v75, v71
	v_add_f32_e32 v5, v70, v5
	v_mul_f32_e32 v9, v73, v5
	v_mov_b32_dpp v70, v66 row_ror:2 row_mask:0xf bank_mask:0xf
	v_mov_b32_dpp v5, v66 row_ror:1 row_mask:0xf bank_mask:0xf
	v_cndmask_b32_e64 v73, v70, v91, s[8:9]
	v_cndmask_b32_e64 v115, v5, v90, s[6:7]
	v_mov_b32_e32 v70, v66
	v_mov_b32_e32 v71, v102
	v_pk_mul_f32 v[70:71], v[70:71], v[114:115]
	v_mov_b32_e32 v66, v67
	v_fma_f32 v5, v98, v73, v71
	v_add_f32_e32 v5, v70, v5
	v_mul_f32_e32 v69, v69, v5
	v_mov_b32_dpp v70, v67 row_ror:2 row_mask:0xf bank_mask:0xf
	v_mov_b32_dpp v5, v67 row_ror:1 row_mask:0xf bank_mask:0xf
	v_cndmask_b32_e64 v5, v5, v82, s[6:7]
	v_mov_b32_e32 v67, v103
	v_pk_mul_f32 v[66:67], v[66:67], v[4:5]
	v_cndmask_b32_e64 v5, v70, v92, s[8:9]
	v_fma_f32 v5, v99, v5, v67
	v_add_f32_e32 v5, v66, v5
	v_mul_f32_e32 v5, v72, v5
	v_cvt_pk_bf16_f32 v66, v74, v9
	v_cvt_pk_bf16_f32 v67, v69, v5
	v_mul_f32_e32 v5, 0xbfb8aa3b, v52
	v_exp_f32_e32 v5, v5
	v_mul_f32_e32 v9, 0xbfb8aa3b, v53
	v_ashrrev_i32_e32 v69, 31, v68
	v_exp_f32_e32 v9, v9
	v_lshlrev_b64 v[68:69], 11, v[68:69]
	v_lshl_add_u64 v[68:69], s[28:29], 0, v[68:69]
	v_lshl_add_u64 v[68:69], v[68:69], 0, v[106:107]
	v_add_f32_e32 v5, 1.0, v5
	global_store_dwordx2 v[68:69], v[66:67], off
	v_rcp_f32_e32 v66, v5
	v_add_f32_e32 v5, 1.0, v9
	v_mul_f32_e32 v9, 0xbfb8aa3b, v54
	v_exp_f32_e32 v9, v9
	v_mul_f32_e32 v67, 0xbfb8aa3b, v55
	v_exp_f32_e32 v69, v67
	v_rcp_f32_e32 v67, v5
	v_add_f32_e32 v5, 1.0, v9
	v_rcp_f32_e32 v68, v5
	v_add_f32_e32 v5, 1.0, v69
	v_rcp_f32_e32 v69, v5
	v_pk_mul_f32 v[54:55], v[62:63], v[54:55]
	v_pk_mul_f32 v[52:53], v[60:61], v[52:53]
	v_pk_mul_f32 v[48:49], v[56:57], v[48:49]
	v_pk_mul_f32 v[52:53], v[52:53], v[66:67]
	v_pk_mul_f32 v[54:55], v[54:55], v[68:69]
	v_mov_b32_dpp v57, v48 row_ror:1 row_mask:0xf bank_mask:0xf
	v_mov_b32_dpp v56, v48 row_ror:2 row_mask:0xf bank_mask:0xf
	v_mov_b32_dpp v9, v49 row_ror:1 row_mask:0xf bank_mask:0xf
	v_mov_b32_dpp v58, v49 row_ror:2 row_mask:0xf bank_mask:0xf
	v_mov_b32_dpp v60, v50 row_ror:1 row_mask:0xf bank_mask:0xf
	v_mov_b32_dpp v59, v50 row_ror:2 row_mask:0xf bank_mask:0xf
	v_mov_b32_dpp v5, v51 row_ror:1 row_mask:0xf bank_mask:0xf
	v_mov_b32_dpp v61, v51 row_ror:2 row_mask:0xf bank_mask:0xf
	s_and_saveexec_b64 s[14:15], s[68:69]
	s_xor_b64 s[84:85], exec, s[14:15]
	s_cbranch_execz .LBB0_155
	ds_read_b128 v[66:69], v182
	ds_read_b128 v[70:73], v181
	v_mov_b32_e32 v62, v50
	v_mov_b32_e32 v63, v102
	s_waitcnt lgkmcnt(1)
	v_cndmask_b32_e64 v61, v61, v69, s[10:11]
	v_cndmask_b32_e64 v115, v60, v68, s[6:7]
	v_cndmask_b32_e64 v59, v59, v68, s[10:11]
	v_cndmask_b32_e64 v5, v5, v69, s[6:7]
	s_waitcnt lgkmcnt(0)
	v_cndmask_b32_e64 v69, v61, v73, s[6:7]
	v_pk_mul_f32 v[60:61], v[62:63], v[114:115]
	v_cndmask_b32_e64 v59, v59, v72, s[6:7]
	v_fma_f32 v59, v98, v59, v61
	v_add_f32_e32 v59, v60, v59
	v_cndmask_b32_e64 v9, v9, v67, s[6:7]
	v_mov_b32_e32 v60, v49
	v_mov_b32_e32 v61, v101
	v_pk_mul_f32 v[60:61], v[60:61], v[8:9]
	v_cndmask_b32_e64 v9, v58, v67, s[10:11]
	v_cndmask_b32_e64 v9, v9, v71, s[6:7]
	v_fma_f32 v9, v97, v9, v61
	v_add_f32_e32 v9, v60, v9
	v_mul_f32_e32 v54, v54, v59
	v_mul_f32_e32 v9, v53, v9
	v_cndmask_b32_e64 v113, v57, v66, s[6:7]
	v_mov_b32_e32 v58, v48
	v_mov_b32_e32 v59, v100
	v_cndmask_b32_e64 v53, v56, v66, s[10:11]
	v_pk_mul_f32 v[58:59], v[58:59], v[112:113]
	v_cndmask_b32_e64 v53, v53, v70, s[6:7]
	v_fma_f32 v53, v96, v53, v59
	v_add_f32_e32 v53, v58, v53
	v_mul_f32_e32 v56, v52, v53
	v_mov_b32_e32 v52, v51
	v_mov_b32_e32 v53, v103
	v_pk_mul_f32 v[52:53], v[52:53], v[4:5]
	s_nop 0
	v_fma_f32 v5, v99, v69, v53
	v_add_f32_e32 v5, v52, v5
	v_mul_f32_e32 v5, v55, v5
	v_cvt_pk_bf16_f32 v52, v56, v9
	v_cvt_pk_bf16_f32 v53, v54, v5
	v_lshlrev_b64 v[54:55], 11, v[64:65]
	v_lshl_add_u64 v[54:55], s[28:29], 0, v[54:55]
	v_lshl_add_u64 v[54:55], v[170:171], 1, v[54:55]
	v_add_co_u32_e32 v54, vcc, 0x40000, v54
	s_nop 1
	v_addc_co_u32_e32 v55, vcc, 0, v55, vcc
	global_store_dwordx2 v[54:55], v[52:53], off
